# s_setprio 1 for one block per CU during the big-GEMM phases
# baseline (speedup 1.0000x reference)
;   DI bf16* G() const { return (bf16*)(p.ws + WS_G); }
; template <class F>
; DI void xcd_items(int total, const F& f) {
;   const int G = gridDim.x;
;   if ((G & 7) == 0 && (total & 7) == 0) {
;     const int x = blockIdx.x & 7, j = blockIdx.x >> 3, per = total >> 3, gl = G >> 3;
;     for (int q = j; q < per; q += gl) f(x * per + q);
.LBB0_244:
	s_andn2_b64 vcc, exec, s[0:1]
	s_cbranch_vccnz .LBB0_256
	s_lshr_b32 s8, s14, 3
	v_readlane_b32 s0, v252, 59
	s_cmp_ge_u32 s0, s8
	s_cbranch_scc1 .LBB0_256
	v_readlane_b32 vcc_lo, v252, 32
	s_cmp_ge_u32 vcc_lo, 0x10000
	s_cbranch_scc0 .Lgp_a
	s_setprio 1
.Lgp_a:
	v_readlane_b32 s9, v252, 59
	s_branch .LBB0_248

; DI unsigned xb_ld(unsigned* p) { return __hip_atomic_load(p, __ATOMIC_RELAXED, __HIP_MEMORY_SCOPE_AGENT); }
; DI unsigned xb_add(unsigned* p, unsigned v) { return __hip_atomic_fetch_add(p, v, __ATOMIC_RELAXED, __HIP_MEMORY_SCOPE_AGENT); }
; #define XB_SPIN(cond, bar) do { unsigned _sp = 0; while (cond) { __builtin_amdgcn_s_sleep(1); \
;     if ((++_sp & 255u) == 0u) { if (xb_ld(&(bar)[XB_TMO])) break; if (_sp > XB_SPIN_CAP) { atomicAdd(&(bar)[XB_TMO], 1u); break; } } } } while (0)
; DI void xcd_barrier(const XcdBarrier& b) {
;   asm volatile("s_waitcnt vmcnt(0)" ::: "memory");
;   __syncthreads();
;   if (threadIdx.x == 0) {
;     unsigned* bar = b.bar;
;     __builtin_amdgcn_s_waitcnt(0);
;     unsigned nloc = b.st[0], nx = b.st[1];
;     if (nloc == 0u) { xcd_barrier_complete(bar, b.x, nloc, nx); b.st[0] = nloc; b.st[1] = nx; }
;     const unsigned old = xb_add(&bar[XB_XSUB(b.x)], 1u);
;     const unsigned gen = old / nloc;
;     if (old + 1u == (gen + 1u) * nloc) {
;       __builtin_amdgcn_fence(__ATOMIC_RELEASE, "agent");
;       asm volatile("s_waitcnt vmcnt(0)" ::: "memory");
;       const unsigned og = xb_add(&bar[XB_TOP], 1u);
;       const unsigned tg = og / nx;
;       if (og + 1u == (tg + 1u) * nx) xb_add(&bar[XB_TOPGEN], 1u);
;       else XB_SPIN(xb_ld(&bar[XB_TOPGEN]) == tg, bar);
;       __builtin_amdgcn_fence(__ATOMIC_ACQUIRE, "agent");
;       xb_add(&bar[XB_XGEN(b.x)], 1u);
;       asm volatile("s_waitcnt vmcnt(0)" ::: "memory");
;     } else {
;       XB_SPIN(xb_ld(&bar[XB_XGEN(b.x)]) == gen, bar);
;       __builtin_amdgcn_fence(__ATOMIC_ACQUIRE, "agent");
;       asm volatile("s_waitcnt vmcnt(0)" ::: "memory");
;     }
;   }
;   __syncthreads();
; }
.LBB0_256:
	s_setprio 0
	s_getreg_b32 s4, hwreg(HW_REG_XCC_ID, 0, 4)
	s_waitcnt vmcnt(0)
	s_barrier
	s_mov_b64 s[0:1], exec
	v_readlane_b32 s6, v252, 14
	v_readlane_b32 s7, v252, 15
	s_and_b64 s[6:7], s[0:1], s[6:7]
	s_mov_b64 exec, s[6:7]
	s_cbranch_execz .LBB0_308
	s_getreg_b32 s4, hwreg(HW_REG_XCC_ID, 0, 4)
	v_mov_b32_e32 v0, 0x12200
	ds_read_b64 v[2:3], v0
	s_lshl_b32 s4, s4, 8
	s_and_b32 s4, s4, 0xf00
	s_add_u32 s2, s88, s4
	s_addc_u32 s3, s89, 0
	v_mov_b32_e32 v5, 1
	v_mov_b32_e32 v6, 0x1000
	global_atomic_add v5, v6, v5, s[2:3] offset:1024 sc0
	v_readlane_b32 s5, v255, 1
	s_add_i32 s5, s5, 1
	s_nop 0
	v_writelane_b32 v255, s5, 1
	v_mov_b32_e32 v6, 0x3400
	s_waitcnt lgkmcnt(0)
	v_readfirstlane_b32 s6, v2
	v_readfirstlane_b32 s7, v3
	s_mul_i32 s8, s5, s6
	s_mul_i32 s9, s5, s7
	s_mov_b32 s11, 0
	s_waitcnt vmcnt(0)
	v_readfirstlane_b32 s10, v5
	s_add_i32 s10, s10, 1
	s_cmp_lg_u32 s10, s8
	s_cbranch_scc1 .Lsy1_inv
	buffer_wbl2 sc1
	v_mov_b32_e32 v5, 1
	s_waitcnt vmcnt(0)
	global_atomic_add v6, v5, s[88:89]

; DI unsigned xb_ld(unsigned* p) { return __hip_atomic_load(p, __ATOMIC_RELAXED, __HIP_MEMORY_SCOPE_AGENT); }
; DI unsigned xb_add(unsigned* p, unsigned v) { return __hip_atomic_fetch_add(p, v, __ATOMIC_RELAXED, __HIP_MEMORY_SCOPE_AGENT); }
; #define XB_SPIN(cond, bar) do { unsigned _sp = 0; while (cond) { __builtin_amdgcn_s_sleep(1); \
;     if ((++_sp & 255u) == 0u) { if (xb_ld(&(bar)[XB_TMO])) break; if (_sp > XB_SPIN_CAP) { atomicAdd(&(bar)[XB_TMO], 1u); break; } } } } while (0)
; DI void xcd_barrier(const XcdBarrier& b) {
;   asm volatile("s_waitcnt vmcnt(0)" ::: "memory");
;   __syncthreads();
;   if (threadIdx.x == 0) {
;     unsigned* bar = b.bar;
;     __builtin_amdgcn_s_waitcnt(0);
;     unsigned nloc = b.st[0], nx = b.st[1];
;     if (nloc == 0u) { xcd_barrier_complete(bar, b.x, nloc, nx); b.st[0] = nloc; b.st[1] = nx; }
;     const unsigned old = xb_add(&bar[XB_XSUB(b.x)], 1u);
;     const unsigned gen = old / nloc;
;     if (old + 1u == (gen + 1u) * nloc) {
;       __builtin_amdgcn_fence(__ATOMIC_RELEASE, "agent");
;       asm volatile("s_waitcnt vmcnt(0)" ::: "memory");
;       const unsigned og = xb_add(&bar[XB_TOP], 1u);
;       const unsigned tg = og / nx;
;       if (og + 1u == (tg + 1u) * nx) xb_add(&bar[XB_TOPGEN], 1u);
;       else XB_SPIN(xb_ld(&bar[XB_TOPGEN]) == tg, bar);
;       __builtin_amdgcn_fence(__ATOMIC_ACQUIRE, "agent");
;       xb_add(&bar[XB_XGEN(b.x)], 1u);
;       asm volatile("s_waitcnt vmcnt(0)" ::: "memory");
;     } else {
;       XB_SPIN(xb_ld(&bar[XB_XGEN(b.x)]) == gen, bar);
;       __builtin_amdgcn_fence(__ATOMIC_ACQUIRE, "agent");
;       asm volatile("s_waitcnt vmcnt(0)" ::: "memory");
;     }
;   }
;   __syncthreads();
; }
.LBB0_516:
	s_setprio 0
	s_getreg_b32 s4, hwreg(HW_REG_XCC_ID, 0, 4)
	s_waitcnt vmcnt(0)
	s_barrier
	s_mov_b64 s[0:1], exec
	v_readlane_b32 s6, v252, 14
	v_readlane_b32 s7, v252, 15
	s_and_b64 s[6:7], s[0:1], s[6:7]
	s_mov_b64 exec, s[6:7]
	s_cbranch_execz .LBB0_568
	s_getreg_b32 s2, hwreg(HW_REG_XCC_ID, 0, 4)
	v_mov_b32_e32 v0, 0x12200
	ds_read_b64 v[2:3], v0
	s_lshl_b32 s2, s2, 8
	s_and_b32 s2, s2, 0xf00
	s_add_u32 s4, s88, s2
	s_addc_u32 s5, s89, 0
	v_mov_b32_e32 v4, 1
	v_mov_b32_e32 v5, 0x1000
	global_atomic_add v4, v5, v4, s[4:5] offset:1024 sc0
	v_readlane_b32 s6, v255, 1
	s_add_i32 s6, s6, 1
	s_nop 0
	v_writelane_b32 v255, s6, 1
	v_mov_b32_e32 v5, 0x3400
	s_waitcnt lgkmcnt(0)
	v_readfirstlane_b32 s7, v2
	v_readfirstlane_b32 s10, v3
	s_mul_i32 s12, s6, s7
	s_mul_i32 s15, s6, s10
	s_mov_b32 s17, 0
	s_waitcnt vmcnt(0)
	v_readfirstlane_b32 s16, v4
	s_add_i32 s16, s16, 1
	s_cmp_lg_u32 s16, s12
	s_cbranch_scc1 .Lsy5_inv
	buffer_wbl2 sc1
	v_mov_b32_e32 v4, 1
	s_waitcnt vmcnt(0)
	global_atomic_add v5, v4, s[88:89]

;   DI float* MOD() const { return (float*)(p.ws + WS_MOD); }
;   DI float* XC() const { return (float*)(p.ws + WS_XC); }
;   DI bf16* WL() const { return (bf16*)(p.ws + WS_WL); }
;   DI bf16* HY() const { return (bf16*)(p.ws + WS_HY); }
;   DI bf16* G() const { return (bf16*)(p.ws + WS_G); }
; template <class F>
; DI void xcd_items(int total, const F& f) {
;   const int G = gridDim.x;
;   if ((G & 7) == 0 && (total & 7) == 0) {
;     const int x = blockIdx.x & 7, j = blockIdx.x >> 3, per = total >> 3, gl = G >> 3;
;     for (int q = j; q < per; q += gl) f(x * per + q);
; __global__ void __launch_bounds__(NT, 2) fwd_kernel(Params p) {
;     ...
;     mfma_gemm_big(RowPtr{c.HY(), D}, RowPtr{c.WL() + WL_OUT / 2, D}, MLAT, D, D, EpiResid4{p.x, p.ctx, p.out, c.XC(), c.MOD(), l}, lds);
.LBB0_1101:
	s_andn2_b64 vcc, exec, s[0:1]
	s_cbranch_vccnz .LBB0_1113
	v_readlane_b32 s0, v253, 35
	v_readlane_b32 s1, v253, 36
	s_andn2_b64 vcc, exec, s[0:1]
	s_cbranch_vccnz .LBB0_1113
	v_readlane_b32 vcc_lo, v252, 32
	s_cmp_ge_u32 vcc_lo, 0x10000
	s_cbranch_scc0 .Lgp_c
	s_setprio 1
.Lgp_c:
	s_cmp_eq_u32 s86, 0
	s_cselect_b64 s[6:7], -1, 0
	s_mul_i32 s12, s86, 3
	v_readlane_b32 s13, v252, 59
	s_branch .LBB0_1105

;   DI float* MOD() const { return (float*)(p.ws + WS_MOD); }
;   DI float* XC() const { return (float*)(p.ws + WS_XC); }
;   DI bf16* WL() const { return (bf16*)(p.ws + WS_WL); }
;   DI bf16* HY() const { return (bf16*)(p.ws + WS_HY); }
; __global__ void __launch_bounds__(NT, 2) fwd_kernel(Params p) {
;     ...
;     if (rows_out > MLAT)
;       for (int t = blockIdx.x; t < 32; t += gridDim.x)
;         mfma_gemm_tile<0>(RowPtr{c.HY(), D}, RowPtr{c.WL() + WL_OUT / 2, D}, MLAT + (t >> 3) * 128, (t & 7) * 128, D, EpiResid4{p.x, p.ctx, p.out, c.XC(), c.MOD(), l}, lds);
.LBB0_1113:
	s_setprio 0
	s_cmp_gt_u32 s86, 1
	v_readlane_b32 s2, v253, 41
	s_cselect_b64 s[0:1], -1, 0
	v_readlane_b32 s3, v253, 42
	s_or_b64 s[0:1], s[0:1], s[2:3]
	s_and_b64 vcc, exec, s[0:1]
	s_cbranch_vccnz .LBB0_1118
	s_cmp_eq_u32 s86, 0
	v_readlane_b32 s0, v252, 35
	s_cselect_b64 vcc, -1, 0
	s_mul_i32 s6, s86, 3
	v_readlane_b32 s7, v254, 7
	v_readlane_b32 s8, v254, 4
	s_mov_b32 s9, s0
	s_mov_b64 s[16:17], 0x80
	v_readlane_b32 s1, v252, 36
